# v049_attnperm
# baseline (speedup 1.0000x reference)
; __device__ __forceinline__ void attn_wave_item(const Params& p, int witem, const int tidx) {
;     ...
;     u32x4 vf[8], kn[8];
;     {
;       const int tn = tile > 0 ? tile - 1 : 0;
;       const char* vp = vbase + (size_t)tile * 8192;
;       const char* kp = kbase + (size_t)tn * 8192;
; #pragma unroll
;       for (int i = 0; i < 8; ++i) vf[i] = *reinterpret_cast<const u32x4*>(vp + i * 1024);
; #pragma unroll
;       for (int ks = 0; ks < 8; ++ks) kn[ks] = *reinterpret_cast<const u32x4*>(kp + ks * 1024);
;     }
;     __builtin_amdgcn_sched_barrier(0);
;     f32x16 S, S2;
; #pragma unroll
;     for (int i = 0; i < 16; ++i) { S[i] = 0.f; S2[i] = 0.f; }
; #pragma unroll
;     for (int ks = 0; ks < 8; ks += 2) {
;       u32x4 qa = *reinterpret_cast<const u32x4*>(qlds + ks * 1024);
;       u32x4 qb = *reinterpret_cast<const u32x4*>(qlds + (ks + 1) * 1024);
;       S = __builtin_amdgcn_mfma_f32_32x32x16_bf16(as_bf16x8(kf[ks]), as_bf16x8(qa), S, 0, 0, 0);
;       S2 = __builtin_amdgcn_mfma_f32_32x32x16_bf16(as_bf16x8(kf[ks + 1]), as_bf16x8(qb), S2, 0, 0, 0);
;     }
; #pragma unroll
;     for (int i = 0; i < 16; ++i) S[i] += S2[i];
.LBB0_119:
	ds_read_b128 v[226:229], v173
	ds_read_b128 v[84:87], v173 offset:1024
	ds_read_b128 v[204:207], v173 offset:2048
	ds_read_b128 v[222:225], v173 offset:3072
	v_lshl_add_u64 v[68:69], v[174:175], 0, s[48:49]
	s_mov_b32 s42, 0x20900000
	v_add_co_u32_e64 v72, s[42:43], s42, v68
	v_sub_u32_e64 v162, v169, 1 clamp
	s_nop 0
	v_addc_co_u32_e64 v73, s[42:43], 0, v69, s[42:43]
	s_mov_b32 s42, 0x20901000
	s_nop 0
	v_add_co_u32_e64 v68, s[42:43], s42, v68
	v_lshlrev_b64 v[70:71], 13, v[162:163]
	s_nop 0
	v_addc_co_u32_e64 v69, s[42:43], 0, v69, s[42:43]
	global_load_dwordx4 v[154:157], v[72:73], off offset:1024
	global_load_dwordx4 v[150:153], v[72:73], off offset:2048
	global_load_dwordx4 v[142:145], v[72:73], off offset:3072
	global_load_dwordx4 v[158:161], v[68:69], off offset:-4096
	global_load_dwordx4 v[146:149], v[68:69], off
	global_load_dwordx4 v[138:141], v[68:69], off offset:1024
	global_load_dwordx4 v[134:137], v[68:69], off offset:2048
	global_load_dwordx4 v[130:133], v[68:69], off offset:3072
	s_waitcnt vmcnt(12)
	v_mov_b64_e32 v[198:199], v[112:113]
	v_mov_b64_e32 v[202:203], v[108:109]
	v_mov_b64_e32 v[80:81], v[102:103]
	v_mov_b64_e32 v[64:65], v[98:99]
	v_lshl_add_u64 v[68:69], v[170:171], 0, v[70:71]
	v_mov_b64_e32 v[196:197], v[110:111]
	v_mov_b64_e32 v[200:201], v[106:107]
	v_mov_b64_e32 v[82:83], v[104:105]
	v_mov_b64_e32 v[66:67], v[100:101]
	global_load_dwordx4 v[98:101], v[68:69], off
	global_load_dwordx4 v[102:105], v[68:69], off offset:1024
	global_load_dwordx4 v[106:109], v[68:69], off offset:2048
	global_load_dwordx4 v[110:113], v[68:69], off offset:3072
	v_add_co_u32_e64 v68, s[42:43], s58, v68
	s_waitcnt vmcnt(12)
	v_mov_b64_e32 v[182:183], v[128:129]
	v_mov_b64_e32 v[186:187], v[124:125]
	v_mov_b64_e32 v[190:191], v[120:121]
	v_mov_b64_e32 v[194:195], v[116:117]
	v_addc_co_u32_e64 v69, s[42:43], 0, v69, s[42:43]
	v_mov_b64_e32 v[180:181], v[126:127]
	v_mov_b64_e32 v[184:185], v[122:123]
	v_mov_b64_e32 v[188:189], v[118:119]
	v_mov_b64_e32 v[192:193], v[114:115]
	global_load_dwordx4 v[114:117], v[68:69], off
	global_load_dwordx4 v[118:121], v[68:69], off offset:1024
	global_load_dwordx4 v[122:125], v[68:69], off offset:2048
	global_load_dwordx4 v[126:129], v[68:69], off offset:3072
	s_cmp_lg_u32 s48, 0
	s_cselect_b64 s[50:51], -1, 0
	s_waitcnt lgkmcnt(3)
	s_setprio 1
	v_mfma_f32_32x32x16_bf16 v[64:79], v[64:67], v[226:229], 0
	s_or_b64 s[44:45], s[6:7], s[50:51]
	s_waitcnt lgkmcnt(2)
	v_mfma_f32_32x32x16_bf16 v[80:95], v[80:83], v[84:87], 0
	s_waitcnt lgkmcnt(1)
	v_mfma_f32_32x32x16_bf16 v[64:79], v[200:203], v[204:207], v[64:79]
	s_waitcnt lgkmcnt(0)
	v_mfma_f32_32x32x16_bf16 v[80:95], v[196:199], v[222:225], v[80:95]
	ds_read_b128 v[196:199], v173 offset:4096
	ds_read_b128 v[200:203], v173 offset:5120
	s_waitcnt lgkmcnt(1)
	v_mfma_f32_32x32x16_bf16 v[64:79], v[192:195], v[196:199], v[64:79]
	s_waitcnt lgkmcnt(0)
	v_mfma_f32_32x32x16_bf16 v[80:95], v[188:191], v[200:203], v[80:95]
	ds_read_b128 v[188:191], v173 offset:6144
	ds_read_b128 v[192:195], v173 offset:7168
	s_waitcnt lgkmcnt(1)
	v_mfma_f32_32x32x16_bf16 v[64:79], v[184:187], v[188:191], v[64:79]
	s_waitcnt lgkmcnt(0)
	v_mfma_f32_32x32x16_bf16 v[80:95], v[180:183], v[192:195], v[80:95]
	s_setprio 0
	s_nop 11
	v_add_f32_e32 v64, v64, v80
	v_exp_f32_e64 v80, -|v64|
	v_add_f32_e32 v65, v65, v81
	v_add_f32_e32 v66, v66, v82
	v_exp_f32_e64 v82, -|v65|
	v_add_f32_e32 v81, 1.0, v80
	v_rcp_f32_e32 v81, v81
	v_add_f32_e32 v67, v67, v83
	v_add_f32_e32 v83, 1.0, v82
	v_cmp_le_f32_e64 s[42:43], 0, v64
	v_mul_f32_e32 v80, v80, v81
	v_rcp_f32_e32 v83, v83
	v_cndmask_b32_e64 v64, v80, v81, s[42:43]
	v_add_f32_e32 v68, v68, v84
	v_cndmask_b32_e64 v84, 0, v64, s[44:45]
	v_cndmask_b32_e64 v64, v81, v80, s[42:43]
	v_exp_f32_e64 v81, -|v66|
	v_cndmask_b32_e64 v80, 1.0, v64, s[44:45]
	v_mul_f32_e32 v64, v82, v83
	v_cmp_le_f32_e64 s[42:43], 0, v65
	s_or_b64 s[44:45], s[8:9], s[50:51]
	v_add_f32_e32 v69, v69, v85
	v_cndmask_b32_e64 v65, v64, v83, s[42:43]
	v_cndmask_b32_e64 v64, v83, v64, s[42:43]
	v_cndmask_b32_e64 v82, 0, v65, s[44:45]
	v_add_f32_e32 v65, 1.0, v81
	v_cndmask_b32_e64 v83, 1.0, v64, s[44:45]
	v_exp_f32_e64 v64, -|v67|
	v_rcp_f32_e32 v65, v65
	v_cmp_le_f32_e64 s[42:43], 0, v66
	s_or_b64 s[44:45], s[10:11], s[50:51]
	v_add_f32_e32 v85, 1.0, v64
	v_mul_f32_e32 v81, v81, v65
	v_rcp_f32_e32 v85, v85
	v_cndmask_b32_e64 v66, v81, v65, s[42:43]
	v_cndmask_b32_e64 v65, v65, v81, s[42:43]
	v_cndmask_b32_e64 v81, 1.0, v65, s[44:45]
	v_exp_f32_e64 v65, -|v68|
	v_mul_f32_e32 v64, v64, v85
	v_cmp_le_f32_e64 s[42:43], 0, v67
	v_exp_f32_e64 v67, -|v69|
	v_add_f32_e32 v70, v70, v86
	v_cndmask_b32_e64 v86, 0, v66, s[44:45]
	v_cndmask_b32_e64 v66, v64, v85, s[42:43]
	s_or_b64 s[44:45], s[12:13], s[50:51]
	v_add_f32_e32 v71, v71, v87
	v_cndmask_b32_e64 v87, 0, v66, s[44:45]
	v_add_f32_e32 v66, 1.0, v65
	v_rcp_f32_e32 v66, v66
	v_cndmask_b32_e64 v64, v85, v64, s[42:43]
	v_cmp_le_f32_e64 s[42:43], 0, v68
	v_add_f32_e32 v68, 1.0, v67
	v_rcp_f32_e32 v68, v68
	v_cndmask_b32_e64 v85, 1.0, v64, s[44:45]
	v_mul_f32_e32 v64, v65, v66
	v_cndmask_b32_e64 v65, v64, v66, s[42:43]
	s_or_b64 s[44:45], s[14:15], s[50:51]
	v_add_f32_e32 v72, v72, v88
	v_cndmask_b32_e64 v88, 0, v65, s[44:45]
	v_mul_f32_e32 v65, v67, v68
	v_exp_f32_e64 v67, -|v70|
	v_cndmask_b32_e64 v64, v66, v64, s[42:43]
	v_cmp_le_f32_e64 s[42:43], 0, v69
	v_cndmask_b32_e64 v64, 1.0, v64, s[44:45]
	s_or_b64 s[44:45], s[16:17], s[50:51]
	v_cndmask_b32_e64 v66, v65, v68, s[42:43]
	v_add_f32_e32 v73, v73, v89
	v_cndmask_b32_e64 v89, 0, v66, s[44:45]
	v_add_f32_e32 v66, 1.0, v67
	v_cndmask_b32_e64 v65, v68, v65, s[42:43]
; __device__ __forceinline__ void attn_wave_item(const Params& p, int witem, const int tidx) {
;     ...
;     for (int r = 0; r < 16; ++r) {
;       float z = S[r];
;       float e = __builtin_amdgcn_exp2f(-fabsf(z));
;       float rr = __builtin_amdgcn_rcpf(1.f + e);
;       float sm = e * rr;
;       int kl = (r & 3) + 8 * (r >> 2) + 4 * half;
;       bool v = !diag || (kl < n);
;       bool pos = z >= 0.f;
;       be[r] = v ? (pos ? rr : sm) : 0.f;
;       om[r] = v ? (pos ? sm : rr) : 1.f;
;     }
;     float gp[4], pgp[4];
; #pragma unroll
;     for (int gi = 0; gi < 4; ++gi) {
;       gp[gi] = (om[4 * gi] * om[4 * gi + 1]) * (om[4 * gi + 2] * om[4 * gi + 3]);
;       pgp[gi] = __shfl_xor(gp[gi], 32, 64);
;     }
;     float w[16];
;     float run = R;
; #pragma unroll
;     ...
;       float a = (half == 0) ? (run * pgp[gi]) : run;
; #pragma unroll
;       for (int r = 3; r >= 0; --r) {
;         int ri = 4 * gi + r;
;         w[ri] = be[ri] * a;
;         a *= om[ri];
;       }
;       run *= gp[gi] * pgp[gi];
;     }
;     R = run;
;     __builtin_amdgcn_sched_barrier(0);
;     bf16x8 pf[2];
; #pragma unroll
;     for (int m = 0; m < 2; ++m) {
;       u32x4 t;
;       t.x = pack2(w[8 * m + 0], w[8 * m + 1]);
;       t.y = pack2(w[8 * m + 2], w[8 * m + 3]);
;       t.z = pack2(w[8 * m + 4], w[8 * m + 5]);
;       t.w = pack2(w[8 * m + 6], w[8 * m + 7]);
;       pf[m] = as_bf16x8(t);
;     }
; #pragma unroll
;     for (int dt = 0; dt < 4; ++dt)
; #pragma unroll
;       for (int m = 0; m < 2; ++m) O[dt] = __builtin_amdgcn_mfma_f32_32x32x16_bf16(as_bf16x8(vf[dt * 2 + m]), pf[m], O[dt], 0, 0, 0);
;     if (__all(R < 1.17549435e-38f)) break;
;     __builtin_amdgcn_sched_barrier(0);
; #pragma unroll
;     for (int i = 0; i < 8; ++i) kf[i] = kn[i];
;   }
	v_rcp_f32_e32 v69, v66
	v_cndmask_b32_e64 v66, 1.0, v65, s[44:45]
	v_exp_f32_e64 v65, -|v71|
	v_cmp_le_f32_e64 s[42:43], 0, v70
	v_mul_f32_e32 v67, v67, v69
	s_or_b64 s[44:45], s[18:19], s[50:51]
	v_add_f32_e32 v70, 1.0, v65
	v_rcp_f32_e32 v70, v70
	v_cndmask_b32_e64 v68, v67, v69, s[42:43]
	v_cndmask_b32_e64 v67, v69, v67, s[42:43]
	v_cndmask_b32_e64 v176, 1.0, v67, s[44:45]
	v_exp_f32_e64 v67, -|v72|
	v_mul_f32_e32 v65, v65, v70
	v_cmp_le_f32_e64 s[42:43], 0, v71
	v_add_f32_e32 v74, v74, v90
	v_cndmask_b32_e64 v90, 0, v68, s[44:45]
	v_cndmask_b32_e64 v68, v65, v70, s[42:43]
	s_or_b64 s[44:45], s[20:21], s[50:51]
	v_cndmask_b32_e64 v71, 0, v68, s[44:45]
	v_add_f32_e32 v68, 1.0, v67
	v_cndmask_b32_e64 v65, v70, v65, s[42:43]
	v_rcp_f32_e32 v69, v68
	v_cndmask_b32_e64 v68, 1.0, v65, s[44:45]
	v_exp_f32_e64 v65, -|v73|
	v_cmp_le_f32_e64 s[42:43], 0, v72
	v_mul_f32_e32 v67, v67, v69
	s_or_b64 s[44:45], s[22:23], s[50:51]
	v_add_f32_e32 v72, 1.0, v65
	v_rcp_f32_e32 v72, v72
	v_cndmask_b32_e64 v70, v67, v69, s[42:43]
	v_cndmask_b32_e64 v67, v69, v67, s[42:43]
	v_cmp_le_f32_e64 s[42:43], 0, v73
	v_mul_f32_e32 v65, v65, v72
	v_add_f32_e32 v75, v75, v91
	v_cndmask_b32_e64 v91, 0, v70, s[44:45]
	v_cndmask_b32_e64 v67, 1.0, v67, s[44:45]
	v_exp_f32_e64 v69, -|v74|
	v_cndmask_b32_e64 v70, v65, v72, s[42:43]
	s_or_b64 s[44:45], s[24:25], s[50:51]
	v_cndmask_b32_e64 v65, v72, v65, s[42:43]
	v_add_f32_e32 v77, v77, v93
	v_cndmask_b32_e64 v93, 1.0, v65, s[44:45]
	v_exp_f32_e64 v65, -|v75|
	v_add_f32_e32 v76, v76, v92
	v_cndmask_b32_e64 v92, 0, v70, s[44:45]
	v_add_f32_e32 v70, 1.0, v69
	v_rcp_f32_e32 v70, v70
	v_add_f32_e32 v73, 1.0, v65
	v_rcp_f32_e32 v73, v73
	v_cmp_le_f32_e64 s[42:43], 0, v74
	v_mul_f32_e32 v69, v69, v70
	s_or_b64 s[44:45], s[26:27], s[50:51]
	v_cndmask_b32_e64 v72, v69, v70, s[42:43]
	v_cndmask_b32_e64 v69, v70, v69, s[42:43]
	v_mul_f32_e32 v65, v65, v73
	v_cmp_le_f32_e64 s[42:43], 0, v75
	v_add_f32_e32 v78, v78, v94
	v_add_f32_e32 v79, v79, v95
	v_cndmask_b32_e64 v94, 0, v72, s[44:45]
	v_cndmask_b32_e64 v95, 1.0, v69, s[44:45]
	v_exp_f32_e64 v69, -|v76|
	v_cndmask_b32_e64 v70, v65, v73, s[42:43]
	s_or_b64 s[44:45], s[28:29], s[50:51]
	v_cndmask_b32_e64 v65, v73, v65, s[42:43]
	v_cndmask_b32_e64 v179, 1.0, v65, s[44:45]
	v_exp_f32_e64 v65, -|v77|
	v_cndmask_b32_e64 v162, 0, v70, s[44:45]
	v_add_f32_e32 v70, 1.0, v69
	v_rcp_f32_e32 v70, v70
	v_add_f32_e32 v73, 1.0, v65
	v_rcp_f32_e32 v73, v73
	v_cmp_le_f32_e64 s[42:43], 0, v76
	v_mul_f32_e32 v69, v69, v70
	s_or_b64 s[44:45], s[30:31], s[50:51]
	v_cndmask_b32_e64 v72, v69, v70, s[42:43]
	v_cndmask_b32_e64 v69, v70, v69, s[42:43]
	v_mul_f32_e32 v65, v65, v73
	v_cmp_le_f32_e64 s[42:43], 0, v77
	v_cndmask_b32_e64 v74, 0, v72, s[44:45]
	v_cndmask_b32_e64 v69, 1.0, v69, s[44:45]
	v_exp_f32_e64 v70, -|v78|
	v_cndmask_b32_e64 v72, v65, v73, s[42:43]
	s_or_b64 s[44:45], s[34:35], s[50:51]
	v_cndmask_b32_e64 v65, v73, v65, s[42:43]
	v_cndmask_b32_e64 v73, 1.0, v65, s[44:45]
	v_exp_f32_e64 v65, -|v79|
	v_cndmask_b32_e64 v75, 0, v72, s[44:45]
	v_add_f32_e32 v72, 1.0, v70
	v_rcp_f32_e32 v72, v72
	v_add_f32_e32 v77, 1.0, v65
	v_rcp_f32_e32 v77, v77
	v_cmp_le_f32_e64 s[42:43], 0, v78
	v_mul_f32_e32 v70, v70, v72
	s_or_b64 s[44:45], s[36:37], s[50:51]
	v_cndmask_b32_e64 v76, v70, v72, s[42:43]
	v_cndmask_b32_e64 v70, v72, v70, s[42:43]
	v_mul_f32_e32 v65, v65, v77
	v_cmp_le_f32_e64 s[42:43], 0, v79
	v_cndmask_b32_e64 v76, 0, v76, s[44:45]
	v_cndmask_b32_e64 v78, 1.0, v70, s[44:45]
	v_cndmask_b32_e64 v70, v65, v77, s[42:43]
	s_or_b64 s[44:45], s[38:39], s[50:51]
	v_cndmask_b32_e64 v65, v77, v65, s[42:43]
	v_cndmask_b32_e64 v77, 1.0, v65, s[44:45]
	v_mul_f32_e32 v65, v69, v73
	v_mul_f32_e32 v69, v78, v77
	v_mul_f32_e32 v69, v65, v69
	v_cndmask_b32_e64 v79, 0, v70, s[44:45]
	v_mul_f32_e32 v70, v80, v83
	v_mov_b32_e32 v250, v69
	v_mov_b32_e32 v251, v69
	s_nop 1
	v_permlane32_swap_b32 v250, v251
	v_cndmask_b32_e32 v80, v250, v251, vcc
	v_mul_f32_e32 v65, v67, v93
	v_mul_f32_e32 v67, v95, v179
	v_mul_f32_e32 v65, v65, v67
	v_mov_b32_e32 v250, v65
	v_mov_b32_e32 v251, v65
	s_nop 1
	v_permlane32_swap_b32 v250, v251
	v_cndmask_b32_e32 v67, v250, v251, vcc
	s_waitcnt lgkmcnt(1)
	v_mul_f32_e32 v180, v177, v80
	v_cndmask_b32_e32 v180, v177, v180, vcc
	v_mul_f32_e32 v77, v180, v77
	v_mul_f32_e32 v76, v76, v77
	v_mul_f32_e32 v77, v78, v77
	v_mul_f32_e32 v73, v73, v77
	v_mul_f32_e32 v69, v69, v80
	v_mul_f32_e32 v78, v75, v77
	v_mul_f32_e32 v77, v74, v73
	v_pk_mul_f32 v[74:75], v[176:177], v[68:69]
	s_waitcnt lgkmcnt(0)
	v_pk_mul_f32 v[64:65], v[64:65], v[66:67]
	v_mul_f32_e32 v67, v75, v67
	v_pk_mul_f32 v[64:65], v[64:65], v[74:75]
	v_mov_b32_e32 v250, v64
	v_mov_b32_e32 v251, v64
	s_nop 1
	v_permlane32_swap_b32 v250, v251
	v_cndmask_b32_e32 v73, v250, v251, vcc
	v_cndmask_b32_e32 v67, v75, v67, vcc
	v_mul_f32_e32 v74, v162, v67
	v_mul_f32_e32 v67, v179, v67
	v_mul_f32_e32 v75, v94, v67
	v_mul_f32_e32 v67, v95, v67
	v_mul_f32_e32 v80, v92, v67
	v_mul_f32_e32 v67, v93, v67
	v_mul_f32_e32 v91, v91, v67
	s_waitcnt lgkmcnt(0)
	v_mul_f32_e32 v67, v65, v73
	v_cndmask_b32_e32 v67, v65, v67, vcc
	v_mul_f32_e32 v72, v81, v85
	v_mul_f32_e32 v92, v71, v67
	v_mov_b32_e32 v71, v64
	v_mul_f32_e32 v67, v68, v67
	v_pk_mul_f32 v[68:69], v[70:71], v[72:73]
	v_mov_b32_e32 v250, v68
	v_mov_b32_e32 v251, v68
	s_nop 1
	v_permlane32_swap_b32 v250, v251
	v_cndmask_b32_e32 v64, v250, v251, vcc
	v_mul_f32_e32 v90, v90, v67
	v_mul_f32_e32 v67, v176, v67
	v_mul_f32_e32 v70, v89, v67
	v_mul_f32_e32 v66, v66, v67
	s_waitcnt lgkmcnt(0)
	v_pk_mul_f32 v[72:73], v[68:69], v[64:65]
	v_mul_f32_e32 v79, v180, v79
	v_mul_f32_e32 v64, v73, v64
	v_cndmask_b32_e32 v64, v73, v64, vcc
	v_mul_f32_e32 v65, v87, v64
	v_mul_f32_e32 v64, v85, v64
	v_mul_f32_e32 v67, v86, v64
	v_mul_f32_e32 v64, v81, v64
	v_mul_f32_e32 v68, v82, v64
	v_mul_f32_e32 v64, v83, v64
	v_mul_f32_e32 v66, v88, v66
	v_mul_f32_e32 v64, v84, v64
	v_cvt_pk_bf16_f32 v64, v64, v68
	v_cvt_pk_bf16_f32 v65, v67, v65
	v_cvt_pk_bf16_f32 v66, v66, v70
	v_cvt_pk_bf16_f32 v67, v90, v92
	v_cvt_pk_bf16_f32 v68, v91, v80
	v_cvt_pk_bf16_f32 v69, v75, v74
	v_cvt_pk_bf16_f32 v70, v77, v78
	v_cvt_pk_bf16_f32 v71, v76, v79
	v_mul_f32_e32 v177, v72, v73
	s_waitcnt vmcnt(12)
	s_setprio 1
	v_mfma_f32_32x32x16_bf16 v[48:63], v[158:161], v[64:67], v[48:63]
	v_cmp_gt_f32_e64 s[42:43], s1, v177
	s_or_b64 s[92:93], s[92:93], exec
	s_mov_b64 s[44:45], -1
	s_cmp_lg_u64 s[42:43], exec
	v_mfma_f32_32x32x16_bf16 v[32:47], v[150:153], v[64:67], v[32:47]
	s_waitcnt vmcnt(11)
	v_mfma_f32_32x32x16_bf16 v[16:31], v[146:149], v[64:67], v[16:31]
	s_waitcnt vmcnt(9)
	v_mfma_f32_32x32x16_bf16 v[0:15], v[134:137], v[64:67], v[0:15]
	v_mfma_f32_32x32x16_bf16 v[48:63], v[154:157], v[68:71], v[48:63]
	v_mfma_f32_32x32x16_bf16 v[32:47], v[142:145], v[68:71], v[32:47]
	v_mfma_f32_32x32x16_bf16 v[16:31], v[138:141], v[68:71], v[16:31]
	s_waitcnt vmcnt(8)
	v_mfma_f32_32x32x16_bf16 v[0:15], v[130:133], v[68:71], v[0:15]
	s_setprio 0
	s_cbranch_scc1 .LBB0_117
	s_branch .LBB0_118
